# v84 + three redundant workgroup barriers removed per attention unit (second unit-fetch barrier, MoBA post-gating barrier, MoBA end-of-pass barrier)
# speedup vs baseline: 1.0024x; 1.0024x over previous
.LBB0_872:
	s_mov_b64 s[4:5], exec
	v_readlane_b32 s2, v240, 3
	v_readlane_b32 s3, v240, 4
	s_and_b64 s[2:3], s[4:5], s[2:3]
	s_mov_b64 exec, s[2:3]
	v_mov_b32_e32 v0, s14
	ds_write_b32 v0, v139
	s_or_b64 exec, exec, s[4:5]
	v_mov_b32_e32 v0, s14
	s_waitcnt lgkmcnt(0)
	s_barrier
	ds_read_b32 v0, v0
	s_movk_i32 s2, 0x3ff
	s_mov_b64 s[12:13], -1
	s_waitcnt lgkmcnt(0)
	v_cmp_lt_i32_e32 vcc, s2, v0
	v_readfirstlane_b32 s1, v0
	s_cbranch_vccz .LBB0_877
	s_mov_b64 s[12:13], 0
	s_cmpk_gt_u32 s1, 0x7ff
	s_mov_b64 s[4:5], 0
	s_cbranch_scc1 .LBB0_877
	s_add_i32 s0, s1, 0xfffffc00
	s_lshr_b32 s0, s0, 5
	s_sub_i32 s93, 31, s0
	s_and_b32 s0, s1, 31
	s_mov_b32 s55, 0
	s_mov_b64 s[4:5], -1

.LBB0_903:
	v_cndmask_b32_e64 v0, v35, v36, s[6:7]
	v_add_f32_e32 v0, v18, v0
	v_cndmask_b32_e64 v1, v37, v38, s[6:7]
	v_cmp_lg_f32_e32 vcc, s33, v0
	v_add_f32_e32 v1, v17, v1
	v_cndmask_b32_e64 v2, v40, v41, s[6:7]
	v_cndmask_b32_e32 v4, v210, v0, vcc
	v_cmp_gt_f32_e32 vcc, v1, v4
	v_add_f32_e32 v2, v39, v2
	v_cndmask_b32_e64 v3, v43, v44, s[6:7]
	v_cndmask_b32_e32 v4, v4, v1, vcc
	v_cndmask_b32_e64 v5, 0, 1, vcc
	v_cmp_gt_f32_e32 vcc, v2, v4
	v_add_f32_e32 v3, v42, v3
	v_cmp_nlg_f32_e64 s[14:15], s33, v0
	v_cndmask_b32_e32 v4, v4, v2, vcc
	v_cndmask_b32_e64 v5, v5, 2, vcc
	v_cmp_gt_f32_e32 vcc, v3, v4
	s_nop 0
	s_nop 0
	v_cndmask_b32_e32 v4, v4, v3, vcc
	v_cndmask_b32_e64 v5, v5, 3, vcc
	v_cmp_gt_f32_e32 vcc, v45, v4
	s_and_b64 vcc, s[4:5], vcc
	s_nop 0
	v_cndmask_b32_e32 v4, v4, v45, vcc
	v_cndmask_b32_e64 v5, v5, 4, vcc
	v_cmp_gt_f32_e32 vcc, v12, v4
	s_and_b64 vcc, s[24:25], vcc
	s_nop 0
	v_cndmask_b32_e32 v4, v4, v12, vcc
	v_cndmask_b32_e64 v5, v5, 5, vcc
	v_cmp_gt_f32_e32 vcc, v46, v4
	s_and_b64 s[2:3], s[26:27], vcc
	v_cndmask_b32_e64 v4, v5, 6, s[2:3]
	v_cmp_eq_u32_e32 vcc, 0, v4
	v_lshlrev_b32_e64 v5, v4, 1
	s_or_b64 vcc, vcc, s[14:15]
	v_cndmask_b32_e32 v4, v0, v210, vcc
	v_and_b32_e32 v6, 2, v5
	v_cmp_eq_u32_e32 vcc, 0, v6
	v_cmp_gt_f32_e64 s[16:17], v1, v4
	s_and_b64 vcc, vcc, s[16:17]
	v_cndmask_b32_e32 v4, v4, v1, vcc
	v_and_b32_e32 v7, 4, v5
	v_cndmask_b32_e64 v6, 0, 1, vcc
	v_cmp_eq_u32_e32 vcc, 0, v7
	v_cmp_gt_f32_e64 s[16:17], v2, v4
	s_and_b64 vcc, vcc, s[16:17]
	v_cndmask_b32_e32 v4, v4, v2, vcc
	v_and_b32_e32 v7, 8, v5
	v_cmp_eq_u32_e64 s[16:17], 0, v7
	v_cmp_gt_f32_e64 s[18:19], v3, v4
	s_and_b64 s[16:17], s[16:17], s[18:19]
	v_and_b32_e32 v7, 16, v5
	v_cndmask_b32_e64 v4, v4, v3, s[16:17]
	v_cmp_eq_u32_e64 s[18:19], 0, v7
	s_and_b64 s[2:3], s[4:5], s[18:19]
	v_cmp_gt_f32_e64 s[18:19], v45, v4
	s_and_b64 s[18:19], s[2:3], s[18:19]
	v_and_b32_e32 v7, 32, v5
	v_cndmask_b32_e64 v4, v4, v45, s[18:19]
	v_cmp_eq_u32_e64 s[20:21], 0, v7
	s_and_b64 s[2:3], s[24:25], s[20:21]
	v_cmp_gt_f32_e64 s[20:21], v12, v4
	s_and_b64 s[20:21], s[2:3], s[20:21]
	v_and_b32_e32 v7, 64, v5
	v_cndmask_b32_e64 v4, v4, v12, s[20:21]
	v_cmp_eq_u32_e64 s[22:23], 0, v7
	s_and_b64 s[2:3], s[26:27], s[22:23]
	v_cmp_gt_f32_e64 s[22:23], v46, v4
	v_lshlrev_b32_e64 v4, v6, 1
	v_cndmask_b32_e64 v4, v4, 4, vcc
	v_cndmask_b32_e64 v4, v4, 8, s[16:17]
	v_cndmask_b32_e64 v4, v4, 16, s[18:19]
	v_cndmask_b32_e64 v4, v4, 32, s[20:21]
	s_and_b64 s[2:3], s[2:3], s[22:23]
	v_cndmask_b32_e64 v4, v4, 64, s[2:3]
	v_or_b32_e32 v6, v4, v5
	v_and_b32_e32 v7, 1, v6
	v_cmp_eq_u32_e32 vcc, 1, v7
	s_or_b64 vcc, vcc, s[14:15]
	v_bitop3_b32 v7, v4, 2, v5 bitop3:0xc8
	v_cndmask_b32_e32 v0, v0, v210, vcc
	v_cmp_eq_u32_e32 vcc, 0, v7
	v_cmp_gt_f32_e64 s[14:15], v1, v0
	s_and_b64 vcc, vcc, s[14:15]
	v_cndmask_b32_e32 v0, v0, v1, vcc
	v_bitop3_b32 v1, v4, 4, v5 bitop3:0xc8
	v_cndmask_b32_e64 v7, 0, 1, vcc
	v_cmp_eq_u32_e32 vcc, 0, v1
	v_cmp_gt_f32_e64 s[14:15], v2, v0
	s_and_b64 vcc, vcc, s[14:15]
	v_cndmask_b32_e32 v0, v0, v2, vcc
	v_bitop3_b32 v1, v4, 8, v5 bitop3:0xc8
	v_cmp_eq_u32_e64 s[14:15], 0, v1
	v_cmp_gt_f32_e64 s[16:17], v3, v0
	s_and_b64 s[14:15], s[14:15], s[16:17]
	v_bitop3_b32 v1, v4, 16, v5 bitop3:0xc8
	v_cndmask_b32_e64 v0, v0, v3, s[14:15]
	v_cmp_eq_u32_e64 s[16:17], 0, v1
	s_and_b64 s[2:3], s[4:5], s[16:17]
	v_cmp_gt_f32_e64 s[16:17], v45, v0
	s_and_b64 s[16:17], s[2:3], s[16:17]
	v_bitop3_b32 v1, v4, 32, v5 bitop3:0xc8
	v_cndmask_b32_e64 v0, v0, v45, s[16:17]
	v_cmp_eq_u32_e64 s[18:19], 0, v1
	s_and_b64 s[2:3], s[24:25], s[18:19]
	v_cmp_gt_f32_e64 s[18:19], v12, v0
	s_and_b64 s[18:19], s[2:3], s[18:19]
	v_bitop3_b32 v1, v4, 64, v5 bitop3:0xc8
	v_cndmask_b32_e64 v0, v0, v12, s[18:19]
	v_cmp_eq_u32_e64 s[20:21], 0, v1
	s_and_b64 s[2:3], s[26:27], s[20:21]
	v_cmp_gt_f32_e64 s[20:21], v46, v0
	v_lshlrev_b32_e64 v0, v7, 1
	v_cndmask_b32_e64 v0, v0, 4, vcc
	v_cndmask_b32_e64 v0, v0, 8, s[14:15]
	v_cndmask_b32_e64 v0, v0, 16, s[16:17]
	v_cndmask_b32_e64 v0, v0, 32, s[18:19]
	s_and_b64 s[2:3], s[2:3], s[20:21]
	v_cndmask_b32_e64 v0, v0, 64, s[2:3]
	v_or_b32_e32 v146, v0, v6
	s_mov_b64 s[14:15], 0

.LBB0_938:
	v_mov_b32_e32 v32, v147
	v_mov_b32_e32 v33, v147
	s_nop 1
	v_permlane32_swap_b32_e32 v32, v33
	v_cndmask_b32_e64 v32, v32, v33, s[6:7]
	v_add_f32_e32 v32, v147, v32
	v_div_scale_f32 v33, s[4:5], v32, v32, 1.0
	v_rcp_f32_e32 v34, v33
	s_ashr_i32 s2, s0, 3
	s_ashr_i32 s3, s2, 31
	s_lshl_b64 s[2:3], s[2:3], 21
	v_fma_f32 v35, -v33, v34, 1.0
	v_fmac_f32_e32 v34, v35, v34
	v_div_scale_f32 v35, vcc, 1.0, v32, 1.0
	v_mul_f32_e32 v36, v35, v34
	v_fma_f32 v37, -v33, v36, v35
	v_fmac_f32_e32 v36, v37, v34
	v_fma_f32 v33, -v33, v36, v35
	v_div_fmas_f32 v33, v33, v34, v36
	v_div_fixup_f32 v33, v33, v32, 1.0
	v_cmp_lt_f32_e32 vcc, 0, v32
	v_readlane_b32 s1, v240, 36
	s_add_u32 s2, s1, s2
	v_cndmask_b32_e32 v34, 0, v33, vcc
	v_readlane_b32 s1, v240, 37
	v_pk_mul_f32 v[32:33], v[0:1], v[34:35] op_sel_hi:[1,0]
	v_pk_mul_f32 v[0:1], v[16:17], v[34:35] op_sel_hi:[1,0]
	v_pk_mul_f32 v[16:17], v[2:3], v[34:35] op_sel_hi:[1,0]
	v_pk_mul_f32 v[2:3], v[18:19], v[34:35] op_sel_hi:[1,0]
	v_pk_mul_f32 v[18:19], v[4:5], v[34:35] op_sel_hi:[1,0]
	v_pk_mul_f32 v[4:5], v[20:21], v[34:35] op_sel_hi:[1,0]
	v_pk_mul_f32 v[20:21], v[6:7], v[34:35] op_sel_hi:[1,0]
	v_pk_mul_f32 v[6:7], v[22:23], v[34:35] op_sel_hi:[1,0]
	v_pk_mul_f32 v[22:23], v[8:9], v[34:35] op_sel_hi:[1,0]
	v_pk_mul_f32 v[8:9], v[24:25], v[34:35] op_sel_hi:[1,0]
	v_pk_mul_f32 v[24:25], v[10:11], v[34:35] op_sel_hi:[1,0]
	v_pk_mul_f32 v[10:11], v[26:27], v[34:35] op_sel_hi:[1,0]
	v_pk_mul_f32 v[26:27], v[12:13], v[34:35] op_sel_hi:[1,0]
	v_pk_mul_f32 v[12:13], v[28:29], v[34:35] op_sel_hi:[1,0]
	v_pk_mul_f32 v[28:29], v[14:15], v[34:35] op_sel_hi:[1,0]
	v_pk_mul_f32 v[14:15], v[30:31], v[34:35] op_sel_hi:[1,0]
	s_addc_u32 s3, s1, s3
	v_lshlrev_b64 v[30:31], 10, v[128:129]
	s_lshl_b32 s1, s0, 6
	v_lshl_add_u64 v[30:31], s[2:3], 0, v[30:31]
	s_and_b32 s96, s1, 0x1c0
	s_waitcnt lgkmcnt(0)
	s_branch .LBB0_870
